# conv item rewritten with all loads in flight + branch-free swa bias/mask
# speedup vs baseline: 1.0248x; 1.0081x over previous
.LBB0_490:
	v_add_u32_e32 v32, v92, v82
	ds_read_b128 v[32:35], v32
	v_add_u32_e32 v36, v92, v83
	ds_read_b128 v[98:101], v36
	v_add_u32_e32 v97, v92, v84
	s_waitcnt vmcnt(3) lgkmcnt(1)
	v_mfma_f32_32x32x16_bf16 v[32:47], v[32:35], v[48:51], 0
	s_waitcnt vmcnt(2) lgkmcnt(0)
	v_mfma_f32_32x32x16_bf16 v[32:47], v[98:101], v[52:55], v[32:47]
	ds_read_b128 v[98:101], v97
	v_add_u32_e32 v97, v92, v86
	ds_read_b128 v[102:105], v97
	v_mov_b32_e32 v97, 0xff800000
	s_waitcnt vmcnt(1) lgkmcnt(1)
	v_mfma_f32_32x32x16_bf16 v[32:47], v[98:101], v[56:59], v[32:47]
	v_add_u32_e32 v99, s48, v94
	v_add_u32_e32 v100, 27, v95
	v_cmp_lt_u32_e32 vcc, s43, v100
	v_cmp_le_u32_e64 s[0:1], s47, v99
	s_and_b64 s[50:51], vcc, s[0:1]
	v_mov_b32_e32 v98, 0xff800000
	s_waitcnt vmcnt(0) lgkmcnt(0)
	v_mfma_f32_32x32x16_bf16 v[32:47], v[102:105], v[60:63], v[32:47]
	v_add_u32_e32 v180, 27, v95
	v_and_b32_e32 v196, 0x7f, v180
	v_lshl_add_u32 v196, v196, 2, v93
	ds_read_b32 v196, v196
	v_add_u32_e32 v181, 26, v95
	v_and_b32_e32 v197, 0x7f, v181
	v_lshl_add_u32 v197, v197, 2, v93
	ds_read_b32 v197, v197
	v_add_u32_e32 v182, 25, v95
	v_and_b32_e32 v198, 0x7f, v182
	v_lshl_add_u32 v198, v198, 2, v93
	ds_read_b32 v198, v198
	v_add_u32_e32 v183, 24, v95
	v_and_b32_e32 v199, 0x7f, v183
	v_lshl_add_u32 v199, v199, 2, v93
	ds_read_b32 v199, v199
	v_add_u32_e32 v184, 19, v95
	v_and_b32_e32 v200, 0x7f, v184
	v_lshl_add_u32 v200, v200, 2, v93
	ds_read_b32 v200, v200
	v_add_u32_e32 v185, 18, v95
	v_and_b32_e32 v201, 0x7f, v185
	v_lshl_add_u32 v201, v201, 2, v93
	ds_read_b32 v201, v201
	v_add_u32_e32 v186, 17, v95
	v_and_b32_e32 v202, 0x7f, v186
	v_lshl_add_u32 v202, v202, 2, v93
	ds_read_b32 v202, v202
	v_add_u32_e32 v187, 16, v95
	v_and_b32_e32 v203, 0x7f, v187
	v_lshl_add_u32 v203, v203, 2, v93
	ds_read_b32 v203, v203
	v_add_u32_e32 v188, 11, v95
	v_and_b32_e32 v204, 0x7f, v188
	v_lshl_add_u32 v204, v204, 2, v93
	ds_read_b32 v204, v204
	v_add_u32_e32 v189, 10, v95
	v_and_b32_e32 v205, 0x7f, v189
	v_lshl_add_u32 v205, v205, 2, v93
	ds_read_b32 v205, v205
	v_add_u32_e32 v190, 9, v95
	v_and_b32_e32 v206, 0x7f, v190
	v_lshl_add_u32 v206, v206, 2, v93
	ds_read_b32 v206, v206
	v_add_u32_e32 v191, 8, v95
	v_and_b32_e32 v207, 0x7f, v191
	v_lshl_add_u32 v207, v207, 2, v93
	ds_read_b32 v207, v207
	v_add_u32_e32 v192, 3, v95
	v_and_b32_e32 v208, 0x7f, v192
	v_lshl_add_u32 v208, v208, 2, v93
	ds_read_b32 v208, v208
	v_add_u32_e32 v193, 2, v95
	v_and_b32_e32 v209, 0x7f, v193
	v_lshl_add_u32 v209, v209, 2, v93
	ds_read_b32 v209, v209
	v_add_u32_e32 v194, 1, v95
	v_and_b32_e32 v210, 0x7f, v194
	v_lshl_add_u32 v210, v210, 2, v93
	ds_read_b32 v210, v210
	v_mov_b32_e32 v195, v95
	v_and_b32_e32 v211, 0x7f, v195
	v_lshl_add_u32 v211, v211, 2, v93
	ds_read_b32 v211, v211
	s_waitcnt lgkmcnt(0)
	v_fmac_f32_e32 v196, 0x3e000000, v32
	v_fmac_f32_e32 v197, 0x3e000000, v33
	v_fmac_f32_e32 v198, 0x3e000000, v34
	v_fmac_f32_e32 v199, 0x3e000000, v35
	v_fmac_f32_e32 v200, 0x3e000000, v36
	v_fmac_f32_e32 v201, 0x3e000000, v37
	v_fmac_f32_e32 v202, 0x3e000000, v38
	v_fmac_f32_e32 v203, 0x3e000000, v39
	v_fmac_f32_e32 v204, 0x3e000000, v40
	v_fmac_f32_e32 v205, 0x3e000000, v41
	v_fmac_f32_e32 v206, 0x3e000000, v42
	v_fmac_f32_e32 v207, 0x3e000000, v43
	v_fmac_f32_e32 v208, 0x3e000000, v44
	v_fmac_f32_e32 v209, 0x3e000000, v45
	v_fmac_f32_e32 v210, 0x3e000000, v46
	v_fmac_f32_e32 v211, 0x3e000000, v47
	v_mov_b32_e32 v212, 0xff800000
	v_cmp_lt_u32_e32 vcc, s43, v180
	v_cmp_le_u32_e64 s[0:1], s47, v99
	s_and_b64 vcc, vcc, s[0:1]
	v_cndmask_b32_e32 v98, v212, v196, vcc
	v_add_u32_e32 v213, 1, v99
	v_cmp_lt_u32_e32 vcc, s43, v181
	v_cmp_le_u32_e64 s[0:1], s47, v213
	s_and_b64 vcc, vcc, s[0:1]
	v_cndmask_b32_e32 v97, v212, v197, vcc
	v_add_u32_e32 v213, 2, v99
	v_cmp_lt_u32_e32 vcc, s43, v182
	v_cmp_le_u32_e64 s[0:1], s47, v213
	s_and_b64 vcc, vcc, s[0:1]
	v_cndmask_b32_e32 v33, v212, v198, vcc
	v_add_u32_e32 v213, 3, v99
	v_cmp_lt_u32_e32 vcc, s43, v183
	v_cmp_le_u32_e64 s[0:1], s47, v213
	s_and_b64 vcc, vcc, s[0:1]
	v_cndmask_b32_e32 v32, v212, v199, vcc
	v_add_u32_e32 v213, 8, v99
	v_cmp_lt_u32_e32 vcc, s43, v184
	v_cmp_le_u32_e64 s[0:1], s47, v213
	s_and_b64 vcc, vcc, s[0:1]
	v_cndmask_b32_e32 v35, v212, v200, vcc
	v_add_u32_e32 v213, 9, v99
	v_cmp_lt_u32_e32 vcc, s43, v185
	v_cmp_le_u32_e64 s[0:1], s47, v213
	s_and_b64 vcc, vcc, s[0:1]
	v_cndmask_b32_e32 v34, v212, v201, vcc
	v_add_u32_e32 v213, 10, v99
	v_cmp_lt_u32_e32 vcc, s43, v186
	v_cmp_le_u32_e64 s[0:1], s47, v213
	s_and_b64 vcc, vcc, s[0:1]
	v_cndmask_b32_e32 v37, v212, v202, vcc
	v_add_u32_e32 v213, 11, v99
	v_cmp_lt_u32_e32 vcc, s43, v187
	v_cmp_le_u32_e64 s[0:1], s47, v213
	s_and_b64 vcc, vcc, s[0:1]
	v_cndmask_b32_e32 v36, v212, v203, vcc
	v_add_u32_e32 v213, 16, v99
	v_cmp_lt_u32_e32 vcc, s43, v188
	v_cmp_le_u32_e64 s[0:1], s47, v213
	s_and_b64 vcc, vcc, s[0:1]
	v_cndmask_b32_e32 v100, v212, v204, vcc
	v_add_u32_e32 v213, 17, v99
	v_cmp_lt_u32_e32 vcc, s43, v189
	v_cmp_le_u32_e64 s[0:1], s47, v213
	s_and_b64 vcc, vcc, s[0:1]
	v_cndmask_b32_e32 v39, v212, v205, vcc
	v_add_u32_e32 v213, 18, v99
	v_cmp_lt_u32_e32 vcc, s43, v190
	v_cmp_le_u32_e64 s[0:1], s47, v213
	s_and_b64 vcc, vcc, s[0:1]
	v_cndmask_b32_e32 v41, v212, v206, vcc
	v_add_u32_e32 v213, 19, v99
	v_cmp_lt_u32_e32 vcc, s43, v191
	v_cmp_le_u32_e64 s[0:1], s47, v213
	s_and_b64 vcc, vcc, s[0:1]
	v_cndmask_b32_e32 v40, v212, v207, vcc
	v_add_u32_e32 v213, 24, v99
	v_cmp_lt_u32_e32 vcc, s43, v192
	v_cmp_le_u32_e64 s[0:1], s47, v213
	s_and_b64 vcc, vcc, s[0:1]
	v_cndmask_b32_e32 v43, v212, v208, vcc
	v_add_u32_e32 v213, 25, v99
	v_cmp_lt_u32_e32 vcc, s43, v193
	v_cmp_le_u32_e64 s[0:1], s47, v213
	s_and_b64 vcc, vcc, s[0:1]
	v_cndmask_b32_e32 v42, v212, v209, vcc
	v_add_u32_e32 v213, 26, v99
	v_cmp_lt_u32_e32 vcc, s43, v194
	v_cmp_le_u32_e64 s[0:1], s47, v213
	s_and_b64 vcc, vcc, s[0:1]
	v_cndmask_b32_e32 v45, v212, v210, vcc
	v_add_u32_e32 v213, 27, v99
	v_cmp_lt_u32_e32 vcc, s43, v195
	v_cmp_le_u32_e64 s[0:1], s47, v213
	s_and_b64 vcc, vcc, s[0:1]
	v_cndmask_b32_e32 v44, v212, v211, vcc
	v_max3_f32 v38, v98, s33, v97
	v_max3_f32 v38, v38, v33, v32
	v_max3_f32 v38, v38, v35, v34
	v_max3_f32 v38, v38, v37, v36
	v_max3_f32 v38, v38, v100, v39
	v_max3_f32 v38, v38, v41, v40
	v_max3_f32 v38, v38, v43, v42
	v_max3_f32 v38, v38, v45, v44
	ds_bpermute_b32 v46, v80, v38
	s_add_i32 s48, s48, 32
	v_subrev_u32_e32 v95, 32, v95
	s_cmpk_lg_i32 s48, 0xa0
	v_add_u32_e32 v92, 0x1000, v92
	s_waitcnt lgkmcnt(0)
	v_max3_f32 v38, v96, v38, v46
	v_sub_f32_e32 v32, v32, v38
	v_mul_f32_e32 v32, 0x3fb8aa3b, v32
	v_exp_f32_e32 v105, v32
	v_sub_f32_e32 v32, v35, v38
	v_mul_f32_e32 v32, 0x3fb8aa3b, v32
	v_exp_f32_e32 v106, v32
	v_sub_f32_e32 v32, v34, v38
	v_mul_f32_e32 v32, 0x3fb8aa3b, v32
	v_exp_f32_e32 v107, v32
	v_sub_f32_e32 v32, v37, v38
	v_mul_f32_e32 v32, 0x3fb8aa3b, v32
	v_exp_f32_e32 v37, v32
	v_sub_f32_e32 v32, v36, v38
	v_mul_f32_e32 v32, 0x3fb8aa3b, v32
	v_exp_f32_e32 v36, v32
	v_sub_f32_e32 v32, v100, v38
	v_mul_f32_e32 v32, 0x3fb8aa3b, v32
	v_exp_f32_e32 v100, v32
	v_sub_f32_e32 v32, v39, v38
	v_mul_f32_e32 v32, 0x3fb8aa3b, v32
	v_exp_f32_e32 v39, v32
	v_sub_f32_e32 v32, v41, v38
	v_mul_f32_e32 v32, 0x3fb8aa3b, v32
	v_exp_f32_e32 v108, v32
	v_sub_f32_e32 v32, v40, v38
	v_mul_f32_e32 v32, 0x3fb8aa3b, v32
	v_sub_f32_e32 v46, v96, v38
	v_exp_f32_e32 v109, v32
	v_sub_f32_e32 v32, v43, v38
	v_mul_f32_e32 v46, 0x3fb8aa3b, v46
	v_mul_f32_e32 v32, 0x3fb8aa3b, v32
	v_exp_f32_e32 v102, v46
	v_sub_f32_e32 v46, v98, v38
	v_exp_f32_e32 v110, v32
	v_sub_f32_e32 v32, v42, v38
	v_add_u32_e32 v34, -6, v91
	v_mul_f32_e32 v46, 0x3fb8aa3b, v46
	v_mul_f32_e32 v32, 0x3fb8aa3b, v32
	v_xor_b32_e32 v34, v34, v74
	v_add_u32_e32 v35, -4, v91
	v_exp_f32_e32 v101, v46
	v_sub_f32_e32 v46, v97, v38
	v_exp_f32_e32 v111, v32
	v_sub_f32_e32 v32, v45, v38
	v_xor_b32_e32 v35, v35, v74
	v_lshl_add_u32 v34, v34, 3, v81
	v_mul_f32_e32 v46, 0x3fb8aa3b, v46
	v_mul_f32_e32 v32, 0x3fb8aa3b, v32
	ds_read2st64_b64 v[40:43], v34 offset0:64 offset1:96
	v_lshl_add_u32 v34, v35, 3, v81
	v_pk_mul_f32 v[14:15], v[14:15], v[102:103] op_sel_hi:[1,0]
	v_pk_mul_f32 v[12:13], v[12:13], v[102:103] op_sel_hi:[1,0]
	v_pk_mul_f32 v[10:11], v[10:11], v[102:103] op_sel_hi:[1,0]
	v_pk_mul_f32 v[8:9], v[8:9], v[102:103] op_sel_hi:[1,0]
	v_pk_mul_f32 v[6:7], v[6:7], v[102:103] op_sel_hi:[1,0]
	v_pk_mul_f32 v[4:5], v[4:5], v[102:103] op_sel_hi:[1,0]
	v_pk_mul_f32 v[2:3], v[2:3], v[102:103] op_sel_hi:[1,0]
	v_pk_mul_f32 v[0:1], v[0:1], v[102:103] op_sel_hi:[1,0]
	v_exp_f32_e32 v103, v46
	v_exp_f32_e32 v112, v32
	v_sub_f32_e32 v32, v44, v38
	ds_read2st64_b64 v[44:47], v34 offset0:64 offset1:96
	s_waitcnt lgkmcnt(1)
	v_mov_b32_e32 v96, v40
	v_mov_b32_e32 v97, v41
	v_sub_f32_e32 v33, v33, v38
	v_mul_f32_e32 v33, 0x3fb8aa3b, v33
	s_waitcnt lgkmcnt(0)
	v_mov_b32_e32 v98, v44
	v_mov_b32_e32 v99, v45
	v_pk_mul_f32 v[30:31], v[30:31], v[102:103] op_sel_hi:[1,0]
	v_pk_mul_f32 v[28:29], v[28:29], v[102:103] op_sel_hi:[1,0]
	v_pk_mul_f32 v[26:27], v[26:27], v[102:103] op_sel_hi:[1,0]
	v_pk_mul_f32 v[24:25], v[24:25], v[102:103] op_sel_hi:[1,0]
	v_pk_mul_f32 v[22:23], v[22:23], v[102:103] op_sel_hi:[1,0]
	v_pk_mul_f32 v[20:21], v[20:21], v[102:103] op_sel_hi:[1,0]
	v_pk_mul_f32 v[18:19], v[18:19], v[102:103] op_sel_hi:[1,0]
	v_pk_mul_f32 v[16:17], v[16:17], v[102:103] op_sel_hi:[1,0]
	v_add_u32_e32 v40, -2, v91
	v_exp_f32_e32 v104, v33
	v_mul_f32_e32 v113, 0x3fb8aa3b, v32
	v_cvt_pk_bf16_f32 v32, v101, v103
	v_cvt_pk_bf16_f32 v33, v104, v105
	v_cvt_pk_bf16_f32 v34, v106, v107
	v_cvt_pk_bf16_f32 v35, v37, v36
	v_xor_b32_e32 v40, v40, v74
	v_mfma_f32_32x32x16_bf16 v[16:31], v[96:99], v[32:35], v[16:31]
	v_xor_b32_e32 v96, v91, v74
	v_lshl_add_u32 v40, v40, 3, v81
	v_lshl_add_u32 v96, v96, 3, v81
	v_mov_b32_e32 v44, v42
	v_mov_b32_e32 v45, v43
	ds_read2st64_b64 v[40:43], v40 offset0:64 offset1:96
	ds_read2st64_b64 v[96:99], v96 offset0:64 offset1:96
	v_mfma_f32_32x32x16_bf16 v[0:15], v[44:47], v[32:35], v[0:15]
	s_waitcnt lgkmcnt(1)
	v_mov_b32_e32 v32, v40
	v_mov_b32_e32 v33, v41
	s_waitcnt lgkmcnt(0)
	v_mov_b32_e32 v34, v96
	v_mov_b32_e32 v35, v97
	v_fmac_f32_e32 v101, v65, v102
	v_exp_f32_e32 v113, v113
	v_cvt_pk_bf16_f32 v44, v100, v39
	v_cvt_pk_bf16_f32 v45, v108, v109
	v_cvt_pk_bf16_f32 v46, v110, v111
	v_cvt_pk_bf16_f32 v47, v112, v113
	v_mov_b32_e32 v96, v42
	v_mfma_f32_32x32x16_bf16 v[16:31], v[32:35], v[44:47], v[16:31]
	v_add_f32_e32 v32, v103, v101
	v_add_f32_e32 v32, v104, v32
	v_mov_b32_e32 v97, v43
	v_add_f32_e32 v32, v105, v32
	v_add_f32_e32 v32, v106, v32
	v_add_f32_e32 v32, v107, v32
	v_add_f32_e32 v32, v37, v32
	v_add_f32_e32 v32, v36, v32
	v_mfma_f32_32x32x16_bf16 v[0:15], v[96:99], v[44:47], v[0:15]
	v_add_f32_e32 v32, v100, v32
	v_add_f32_e32 v32, v39, v32
	v_add_f32_e32 v32, v108, v32
	v_add_f32_e32 v32, v109, v32
	v_add_f32_e32 v32, v110, v32
	v_add_f32_e32 v32, v111, v32
	v_add_f32_e32 v32, v112, v32
	v_add_f32_e32 v65, v113, v32
	v_add_u32_e32 v91, 8, v91
	s_cbranch_scc0 .LBB0_486
	v_mov_b32_e32 v96, v38
	s_branch .LBB0_490

.LBB0_525:
	s_and_b64 vcc, exec, s[0:1]
	s_cbranch_vccz .LBB0_558
	v_readlane_b32 s28, v243, 52
	v_readlane_b32 s29, v243, 53
	v_readlane_b32 s24, v243, 54
	v_readlane_b32 s25, v243, 55
	v_and_b32_e32 v120, 0x7f, v147
	v_lshlrev_b32_e32 v121, 4, v120
	v_lshlrev_b32_e32 v120, 5, v120
	v_lshrrev_b32_e32 v122, 7, v147
	s_lshl_b32 s0, s34, 5
	s_addk_i32 s0, 0xa000
	v_lshl_add_u32 v122, v122, 3, s0
	s_movk_i32 s30, 0x1400
	v_mul_lo_u32 v123, v122, s30
	v_add_u32_e32 v123, v123, v121
	s_movk_i32 s30, 0xc00
	v_mul_lo_u32 v124, v122, s30
	v_add_u32_e32 v124, v124, v121
	v_mov_b32_e32 v26, 0
	v_mov_b32_e32 v27, 0
	v_mov_b32_e32 v28, 0
	v_mov_b32_e32 v29, 0
	v_mov_b32_e32 v30, 0
	v_mov_b32_e32 v31, 0
	v_mov_b32_e32 v32, 0
	v_mov_b32_e32 v33, 0
	v_mov_b32_e32 v34, 0
	v_mov_b32_e32 v35, 0
	v_mov_b32_e32 v36, 0
	v_mov_b32_e32 v37, 0
	v_mov_b32_e32 v38, 0
	v_mov_b32_e32 v39, 0
	v_mov_b32_e32 v40, 0
	v_mov_b32_e32 v41, 0
	s_waitcnt lgkmcnt(0)
	s_movk_i32 s30, 0x4000
	v_cmp_gt_i32_e64 s[38:39], s30, v122
	v_and_b32_e32 v125, 0x1ff8, v122
	v_cmp_ne_u32_e32 vcc, 0, v125
	s_and_b64 s[0:1], s[38:39], vcc
	s_mov_b64 s[30:31], exec
	s_and_b64 exec, s[30:31], s[0:1]
	s_cbranch_execz .Lconv_pfx_a
	v_add_u32_e32 v125, 0xffffd800, v123
	global_load_dwordx4 v[50:53], v125, s[28:29] offset:2048
	v_add_u32_e32 v125, 0xffffec00, v123
	global_load_dwordx4 v[170:173], v125, s[28:29] offset:2048
.Lconv_pfx_a:
	s_andn2_b64 exec, s[30:31], s[38:39]
	s_cbranch_execz .Lconv_pfx_b
	v_add_u32_e32 v125, 0xffffc000, v122
	v_lshrrev_b32_e32 v125, 2, v125
	v_lshl_add_u32 v125, v125, 12, v120
	global_load_dwordx4 v[26:29], v125, s[20:21]
	global_load_dwordx4 v[30:33], v125, s[20:21] offset:16
	v_add_u32_e32 v125, 0x1000, v125
	global_load_dwordx4 v[34:37], v125, s[20:21]
	global_load_dwordx4 v[38:41], v125, s[20:21] offset:16
.Lconv_pfx_b:
	s_mov_b64 exec, s[30:31]
	global_load_dwordx4 v[2:5], v120, s[10:11]
	global_load_dwordx4 v[6:9], v120, s[10:11] offset:16
	global_load_dwordx4 v[10:13], v120, s[16:17]
	global_load_dwordx4 v[14:17], v120, s[16:17] offset:16
	global_load_dwordx4 v[18:21], v120, s[18:19]
	global_load_dwordx4 v[22:25], v120, s[18:19] offset:16
	global_load_dwordx4 v[56:59], v123, s[28:29]
	global_load_dwordx4 v[60:63], v123, s[28:29] offset:2048
	v_add_u32_e32 v125, 0x1400, v123
	global_load_dwordx4 v[64:67], v125, s[28:29]
	global_load_dwordx4 v[68:71], v125, s[28:29] offset:2048
	v_add_u32_e32 v125, 0x2800, v123
	global_load_dwordx4 v[72:75], v125, s[28:29]
	global_load_dwordx4 v[76:79], v125, s[28:29] offset:2048
	v_add_u32_e32 v125, 0x3c00, v123
	global_load_dwordx4 v[80:83], v125, s[28:29]
	global_load_dwordx4 v[84:87], v125, s[28:29] offset:2048
	v_add_u32_e32 v125, 0x5000, v123
	global_load_dwordx4 v[88:91], v125, s[28:29]
	global_load_dwordx4 v[92:95], v125, s[28:29] offset:2048
	v_add_u32_e32 v125, 0x6400, v123
	global_load_dwordx4 v[96:99], v125, s[28:29]
	global_load_dwordx4 v[100:103], v125, s[28:29] offset:2048
	v_add_u32_e32 v125, 0x7800, v123
	global_load_dwordx4 v[104:107], v125, s[28:29]
	global_load_dwordx4 v[108:111], v125, s[28:29] offset:2048
	v_add_u32_e32 v125, 0x8c00, v123
	global_load_dwordx4 v[112:115], v125, s[28:29]
	global_load_dwordx4 v[116:119], v125, s[28:29] offset:2048
	s_waitcnt vmcnt(16)
	s_and_b64 exec, s[30:31], s[0:1]
	s_cbranch_execz .Lconv_pfx_c
	v_lshlrev_b32_e32 v26, 16, v50
	v_and_b32_e32 v27, 0xffff0000, v50
	v_lshlrev_b32_e32 v34, 16, v170
	v_and_b32_e32 v35, 0xffff0000, v170
	v_lshlrev_b32_e32 v28, 16, v51
	v_and_b32_e32 v29, 0xffff0000, v51
	v_lshlrev_b32_e32 v36, 16, v171
	v_and_b32_e32 v37, 0xffff0000, v171
	v_lshlrev_b32_e32 v30, 16, v52
	v_and_b32_e32 v31, 0xffff0000, v52
	v_lshlrev_b32_e32 v38, 16, v172
	v_and_b32_e32 v39, 0xffff0000, v172
	v_lshlrev_b32_e32 v32, 16, v53
	v_and_b32_e32 v33, 0xffff0000, v53
	v_lshlrev_b32_e32 v40, 16, v173
	v_and_b32_e32 v41, 0xffff0000, v173
.Lconv_pfx_c:
	s_mov_b64 exec, s[30:31]
	s_waitcnt vmcnt(14)
	v_lshlrev_b32_e32 v42, 16, v60
	v_and_b32_e32 v43, 0xffff0000, v60
	v_lshlrev_b32_e32 v126, 16, v56
	v_and_b32_e32 v127, 0xffff0000, v56
	v_lshlrev_b32_e32 v44, 16, v61
	v_and_b32_e32 v45, 0xffff0000, v61
	v_lshlrev_b32_e32 v128, 16, v57
	v_and_b32_e32 v129, 0xffff0000, v57
	v_lshlrev_b32_e32 v46, 16, v62
	v_and_b32_e32 v47, 0xffff0000, v62
	v_lshlrev_b32_e32 v130, 16, v58
	v_and_b32_e32 v131, 0xffff0000, v58
	v_lshlrev_b32_e32 v48, 16, v63
	v_and_b32_e32 v49, 0xffff0000, v63
	v_lshlrev_b32_e32 v132, 16, v59
	v_and_b32_e32 v133, 0xffff0000, v59
	v_pk_mul_f32 v[174:175], v[2:3], v[26:27]
	v_pk_mul_f32 v[176:177], v[4:5], v[28:29]
	v_pk_mul_f32 v[178:179], v[6:7], v[30:31]
	v_pk_mul_f32 v[180:181], v[8:9], v[32:33]
	v_pk_fma_f32 v[174:175], v[10:11], v[34:35], v[174:175]
	v_pk_fma_f32 v[176:177], v[12:13], v[36:37], v[176:177]
	v_pk_fma_f32 v[178:179], v[14:15], v[38:39], v[178:179]
	v_pk_fma_f32 v[180:181], v[16:17], v[40:41], v[180:181]
	v_pk_fma_f32 v[174:175], v[18:19], v[42:43], v[174:175]
	v_pk_fma_f32 v[176:177], v[20:21], v[44:45], v[176:177]
	v_pk_fma_f32 v[178:179], v[22:23], v[46:47], v[178:179]
	v_pk_fma_f32 v[180:181], v[24:25], v[48:49], v[180:181]
	v_pk_mul_f32 v[174:175], v[126:127], v[174:175]
	v_pk_mul_f32 v[176:177], v[128:129], v[176:177]
	v_pk_mul_f32 v[178:179], v[130:131], v[178:179]
	v_pk_mul_f32 v[180:181], v[132:133], v[180:181]
	v_cvt_pk_bf16_f32 v56, v174, v175
	v_cvt_pk_bf16_f32 v57, v176, v177
	v_cvt_pk_bf16_f32 v58, v178, v179
	v_cvt_pk_bf16_f32 v59, v180, v181
	global_store_dwordx4 v124, v[56:59], s[24:25]
	s_waitcnt vmcnt(13)
	v_lshlrev_b32_e32 v26, 16, v68
	v_and_b32_e32 v27, 0xffff0000, v68
	v_lshlrev_b32_e32 v126, 16, v64
	v_and_b32_e32 v127, 0xffff0000, v64
	v_lshlrev_b32_e32 v28, 16, v69
	v_and_b32_e32 v29, 0xffff0000, v69
	v_lshlrev_b32_e32 v128, 16, v65
	v_and_b32_e32 v129, 0xffff0000, v65
	v_lshlrev_b32_e32 v30, 16, v70
	v_and_b32_e32 v31, 0xffff0000, v70
	v_lshlrev_b32_e32 v130, 16, v66
	v_and_b32_e32 v131, 0xffff0000, v66
	v_lshlrev_b32_e32 v32, 16, v71
	v_and_b32_e32 v33, 0xffff0000, v71
	v_lshlrev_b32_e32 v132, 16, v67
	v_and_b32_e32 v133, 0xffff0000, v67
	v_pk_mul_f32 v[174:175], v[2:3], v[34:35]
	v_pk_mul_f32 v[176:177], v[4:5], v[36:37]
	v_pk_mul_f32 v[178:179], v[6:7], v[38:39]
	v_pk_mul_f32 v[180:181], v[8:9], v[40:41]
	v_pk_fma_f32 v[174:175], v[10:11], v[42:43], v[174:175]
	v_pk_fma_f32 v[176:177], v[12:13], v[44:45], v[176:177]
	v_pk_fma_f32 v[178:179], v[14:15], v[46:47], v[178:179]
	v_pk_fma_f32 v[180:181], v[16:17], v[48:49], v[180:181]
	v_pk_fma_f32 v[174:175], v[18:19], v[26:27], v[174:175]
	v_pk_fma_f32 v[176:177], v[20:21], v[28:29], v[176:177]
	v_pk_fma_f32 v[178:179], v[22:23], v[30:31], v[178:179]
	v_pk_fma_f32 v[180:181], v[24:25], v[32:33], v[180:181]
	v_pk_mul_f32 v[174:175], v[126:127], v[174:175]
	v_pk_mul_f32 v[176:177], v[128:129], v[176:177]
	v_pk_mul_f32 v[178:179], v[130:131], v[178:179]
	v_pk_mul_f32 v[180:181], v[132:133], v[180:181]
	v_cvt_pk_bf16_f32 v64, v174, v175
	v_cvt_pk_bf16_f32 v65, v176, v177
	v_cvt_pk_bf16_f32 v66, v178, v179
	v_cvt_pk_bf16_f32 v67, v180, v181
	v_add_u32_e32 v125, 0xc00, v124
	global_store_dwordx4 v125, v[64:67], s[24:25]
	s_waitcnt vmcnt(12)
	v_lshlrev_b32_e32 v34, 16, v76
	v_and_b32_e32 v35, 0xffff0000, v76
	v_lshlrev_b32_e32 v126, 16, v72
	v_and_b32_e32 v127, 0xffff0000, v72
	v_lshlrev_b32_e32 v36, 16, v77
	v_and_b32_e32 v37, 0xffff0000, v77
	v_lshlrev_b32_e32 v128, 16, v73
	v_and_b32_e32 v129, 0xffff0000, v73
	v_lshlrev_b32_e32 v38, 16, v78
	v_and_b32_e32 v39, 0xffff0000, v78
	v_lshlrev_b32_e32 v130, 16, v74
	v_and_b32_e32 v131, 0xffff0000, v74
	v_lshlrev_b32_e32 v40, 16, v79
	v_and_b32_e32 v41, 0xffff0000, v79
	v_lshlrev_b32_e32 v132, 16, v75
	v_and_b32_e32 v133, 0xffff0000, v75
	v_pk_mul_f32 v[174:175], v[2:3], v[42:43]
	v_pk_mul_f32 v[176:177], v[4:5], v[44:45]
	v_pk_mul_f32 v[178:179], v[6:7], v[46:47]
	v_pk_mul_f32 v[180:181], v[8:9], v[48:49]
	v_pk_fma_f32 v[174:175], v[10:11], v[26:27], v[174:175]
	v_pk_fma_f32 v[176:177], v[12:13], v[28:29], v[176:177]
	v_pk_fma_f32 v[178:179], v[14:15], v[30:31], v[178:179]
	v_pk_fma_f32 v[180:181], v[16:17], v[32:33], v[180:181]
	v_pk_fma_f32 v[174:175], v[18:19], v[34:35], v[174:175]
	v_pk_fma_f32 v[176:177], v[20:21], v[36:37], v[176:177]
	v_pk_fma_f32 v[178:179], v[22:23], v[38:39], v[178:179]
	v_pk_fma_f32 v[180:181], v[24:25], v[40:41], v[180:181]
	v_pk_mul_f32 v[174:175], v[126:127], v[174:175]
	v_pk_mul_f32 v[176:177], v[128:129], v[176:177]
	v_pk_mul_f32 v[178:179], v[130:131], v[178:179]
	v_pk_mul_f32 v[180:181], v[132:133], v[180:181]
	v_cvt_pk_bf16_f32 v72, v174, v175
	v_cvt_pk_bf16_f32 v73, v176, v177
	v_cvt_pk_bf16_f32 v74, v178, v179
	v_cvt_pk_bf16_f32 v75, v180, v181
	v_add_u32_e32 v125, 0x1800, v124
	global_store_dwordx4 v125, v[72:75], s[24:25]
	s_waitcnt vmcnt(11)
	v_lshlrev_b32_e32 v42, 16, v84
	v_and_b32_e32 v43, 0xffff0000, v84
	v_lshlrev_b32_e32 v126, 16, v80
	v_and_b32_e32 v127, 0xffff0000, v80
	v_lshlrev_b32_e32 v44, 16, v85
	v_and_b32_e32 v45, 0xffff0000, v85
	v_lshlrev_b32_e32 v128, 16, v81
	v_and_b32_e32 v129, 0xffff0000, v81
	v_lshlrev_b32_e32 v46, 16, v86
	v_and_b32_e32 v47, 0xffff0000, v86
	v_lshlrev_b32_e32 v130, 16, v82
	v_and_b32_e32 v131, 0xffff0000, v82
	v_lshlrev_b32_e32 v48, 16, v87
	v_and_b32_e32 v49, 0xffff0000, v87
	v_lshlrev_b32_e32 v132, 16, v83
	v_and_b32_e32 v133, 0xffff0000, v83
	v_pk_mul_f32 v[174:175], v[2:3], v[26:27]
	v_pk_mul_f32 v[176:177], v[4:5], v[28:29]
	v_pk_mul_f32 v[178:179], v[6:7], v[30:31]
	v_pk_mul_f32 v[180:181], v[8:9], v[32:33]
	v_pk_fma_f32 v[174:175], v[10:11], v[34:35], v[174:175]
	v_pk_fma_f32 v[176:177], v[12:13], v[36:37], v[176:177]
	v_pk_fma_f32 v[178:179], v[14:15], v[38:39], v[178:179]
	v_pk_fma_f32 v[180:181], v[16:17], v[40:41], v[180:181]
	v_pk_fma_f32 v[174:175], v[18:19], v[42:43], v[174:175]
	v_pk_fma_f32 v[176:177], v[20:21], v[44:45], v[176:177]
	v_pk_fma_f32 v[178:179], v[22:23], v[46:47], v[178:179]
	v_pk_fma_f32 v[180:181], v[24:25], v[48:49], v[180:181]
	v_pk_mul_f32 v[174:175], v[126:127], v[174:175]
	v_pk_mul_f32 v[176:177], v[128:129], v[176:177]
	v_pk_mul_f32 v[178:179], v[130:131], v[178:179]
	v_pk_mul_f32 v[180:181], v[132:133], v[180:181]
	v_cvt_pk_bf16_f32 v80, v174, v175
	v_cvt_pk_bf16_f32 v81, v176, v177
	v_cvt_pk_bf16_f32 v82, v178, v179
	v_cvt_pk_bf16_f32 v83, v180, v181
	v_add_u32_e32 v125, 0x2400, v124
	global_store_dwordx4 v125, v[80:83], s[24:25]
	s_waitcnt vmcnt(10)
	v_lshlrev_b32_e32 v26, 16, v92
	v_and_b32_e32 v27, 0xffff0000, v92
	v_lshlrev_b32_e32 v126, 16, v88
	v_and_b32_e32 v127, 0xffff0000, v88
	v_lshlrev_b32_e32 v28, 16, v93
	v_and_b32_e32 v29, 0xffff0000, v93
	v_lshlrev_b32_e32 v128, 16, v89
	v_and_b32_e32 v129, 0xffff0000, v89
	v_lshlrev_b32_e32 v30, 16, v94
	v_and_b32_e32 v31, 0xffff0000, v94
	v_lshlrev_b32_e32 v130, 16, v90
	v_and_b32_e32 v131, 0xffff0000, v90
	v_lshlrev_b32_e32 v32, 16, v95
	v_and_b32_e32 v33, 0xffff0000, v95
	v_lshlrev_b32_e32 v132, 16, v91
	v_and_b32_e32 v133, 0xffff0000, v91
	v_pk_mul_f32 v[174:175], v[2:3], v[34:35]
	v_pk_mul_f32 v[176:177], v[4:5], v[36:37]
	v_pk_mul_f32 v[178:179], v[6:7], v[38:39]
	v_pk_mul_f32 v[180:181], v[8:9], v[40:41]
	v_pk_fma_f32 v[174:175], v[10:11], v[42:43], v[174:175]
	v_pk_fma_f32 v[176:177], v[12:13], v[44:45], v[176:177]
	v_pk_fma_f32 v[178:179], v[14:15], v[46:47], v[178:179]
	v_pk_fma_f32 v[180:181], v[16:17], v[48:49], v[180:181]
	v_pk_fma_f32 v[174:175], v[18:19], v[26:27], v[174:175]
	v_pk_fma_f32 v[176:177], v[20:21], v[28:29], v[176:177]
	v_pk_fma_f32 v[178:179], v[22:23], v[30:31], v[178:179]
	v_pk_fma_f32 v[180:181], v[24:25], v[32:33], v[180:181]
	v_pk_mul_f32 v[174:175], v[126:127], v[174:175]
	v_pk_mul_f32 v[176:177], v[128:129], v[176:177]
	v_pk_mul_f32 v[178:179], v[130:131], v[178:179]
	v_pk_mul_f32 v[180:181], v[132:133], v[180:181]
	v_cvt_pk_bf16_f32 v88, v174, v175
	v_cvt_pk_bf16_f32 v89, v176, v177
	v_cvt_pk_bf16_f32 v90, v178, v179
	v_cvt_pk_bf16_f32 v91, v180, v181
	v_add_u32_e32 v125, 0x3000, v124
	global_store_dwordx4 v125, v[88:91], s[24:25]
	s_waitcnt vmcnt(9)
	v_lshlrev_b32_e32 v34, 16, v100
	v_and_b32_e32 v35, 0xffff0000, v100
	v_lshlrev_b32_e32 v126, 16, v96
	v_and_b32_e32 v127, 0xffff0000, v96
	v_lshlrev_b32_e32 v36, 16, v101
	v_and_b32_e32 v37, 0xffff0000, v101
	v_lshlrev_b32_e32 v128, 16, v97
	v_and_b32_e32 v129, 0xffff0000, v97
	v_lshlrev_b32_e32 v38, 16, v102
	v_and_b32_e32 v39, 0xffff0000, v102
	v_lshlrev_b32_e32 v130, 16, v98
	v_and_b32_e32 v131, 0xffff0000, v98
	v_lshlrev_b32_e32 v40, 16, v103
	v_and_b32_e32 v41, 0xffff0000, v103
	v_lshlrev_b32_e32 v132, 16, v99
	v_and_b32_e32 v133, 0xffff0000, v99
	v_pk_mul_f32 v[174:175], v[2:3], v[42:43]
	v_pk_mul_f32 v[176:177], v[4:5], v[44:45]
	v_pk_mul_f32 v[178:179], v[6:7], v[46:47]
	v_pk_mul_f32 v[180:181], v[8:9], v[48:49]
	v_pk_fma_f32 v[174:175], v[10:11], v[26:27], v[174:175]
	v_pk_fma_f32 v[176:177], v[12:13], v[28:29], v[176:177]
	v_pk_fma_f32 v[178:179], v[14:15], v[30:31], v[178:179]
	v_pk_fma_f32 v[180:181], v[16:17], v[32:33], v[180:181]
	v_pk_fma_f32 v[174:175], v[18:19], v[34:35], v[174:175]
	v_pk_fma_f32 v[176:177], v[20:21], v[36:37], v[176:177]
	v_pk_fma_f32 v[178:179], v[22:23], v[38:39], v[178:179]
	v_pk_fma_f32 v[180:181], v[24:25], v[40:41], v[180:181]
	v_pk_mul_f32 v[174:175], v[126:127], v[174:175]
	v_pk_mul_f32 v[176:177], v[128:129], v[176:177]
	v_pk_mul_f32 v[178:179], v[130:131], v[178:179]
	v_pk_mul_f32 v[180:181], v[132:133], v[180:181]
	v_cvt_pk_bf16_f32 v96, v174, v175
	v_cvt_pk_bf16_f32 v97, v176, v177
	v_cvt_pk_bf16_f32 v98, v178, v179
	v_cvt_pk_bf16_f32 v99, v180, v181
	v_add_u32_e32 v125, 0x3c00, v124
	global_store_dwordx4 v125, v[96:99], s[24:25]
	s_waitcnt vmcnt(8)
	v_lshlrev_b32_e32 v42, 16, v108
	v_and_b32_e32 v43, 0xffff0000, v108
	v_lshlrev_b32_e32 v126, 16, v104
	v_and_b32_e32 v127, 0xffff0000, v104
	v_lshlrev_b32_e32 v44, 16, v109
	v_and_b32_e32 v45, 0xffff0000, v109
	v_lshlrev_b32_e32 v128, 16, v105
	v_and_b32_e32 v129, 0xffff0000, v105
	v_lshlrev_b32_e32 v46, 16, v110
	v_and_b32_e32 v47, 0xffff0000, v110
	v_lshlrev_b32_e32 v130, 16, v106
	v_and_b32_e32 v131, 0xffff0000, v106
	v_lshlrev_b32_e32 v48, 16, v111
	v_and_b32_e32 v49, 0xffff0000, v111
	v_lshlrev_b32_e32 v132, 16, v107
	v_and_b32_e32 v133, 0xffff0000, v107
	v_pk_mul_f32 v[174:175], v[2:3], v[26:27]
	v_pk_mul_f32 v[176:177], v[4:5], v[28:29]
	v_pk_mul_f32 v[178:179], v[6:7], v[30:31]
	v_pk_mul_f32 v[180:181], v[8:9], v[32:33]
	v_pk_fma_f32 v[174:175], v[10:11], v[34:35], v[174:175]
	v_pk_fma_f32 v[176:177], v[12:13], v[36:37], v[176:177]
	v_pk_fma_f32 v[178:179], v[14:15], v[38:39], v[178:179]
	v_pk_fma_f32 v[180:181], v[16:17], v[40:41], v[180:181]
	v_pk_fma_f32 v[174:175], v[18:19], v[42:43], v[174:175]
	v_pk_fma_f32 v[176:177], v[20:21], v[44:45], v[176:177]
	v_pk_fma_f32 v[178:179], v[22:23], v[46:47], v[178:179]
	v_pk_fma_f32 v[180:181], v[24:25], v[48:49], v[180:181]
	v_pk_mul_f32 v[174:175], v[126:127], v[174:175]
	v_pk_mul_f32 v[176:177], v[128:129], v[176:177]
	v_pk_mul_f32 v[178:179], v[130:131], v[178:179]
	v_pk_mul_f32 v[180:181], v[132:133], v[180:181]
	v_cvt_pk_bf16_f32 v104, v174, v175
	v_cvt_pk_bf16_f32 v105, v176, v177
	v_cvt_pk_bf16_f32 v106, v178, v179
	v_cvt_pk_bf16_f32 v107, v180, v181
	v_add_u32_e32 v125, 0x4800, v124
	global_store_dwordx4 v125, v[104:107], s[24:25]
	s_waitcnt vmcnt(7)
	v_lshlrev_b32_e32 v26, 16, v116
	v_and_b32_e32 v27, 0xffff0000, v116
	v_lshlrev_b32_e32 v126, 16, v112
	v_and_b32_e32 v127, 0xffff0000, v112
	v_lshlrev_b32_e32 v28, 16, v117
	v_and_b32_e32 v29, 0xffff0000, v117
	v_lshlrev_b32_e32 v128, 16, v113
	v_and_b32_e32 v129, 0xffff0000, v113
	v_lshlrev_b32_e32 v30, 16, v118
	v_and_b32_e32 v31, 0xffff0000, v118
	v_lshlrev_b32_e32 v130, 16, v114
	v_and_b32_e32 v131, 0xffff0000, v114
	v_lshlrev_b32_e32 v32, 16, v119
	v_and_b32_e32 v33, 0xffff0000, v119
	v_lshlrev_b32_e32 v132, 16, v115
	v_and_b32_e32 v133, 0xffff0000, v115
	v_pk_mul_f32 v[174:175], v[2:3], v[34:35]
	v_pk_mul_f32 v[176:177], v[4:5], v[36:37]
	v_pk_mul_f32 v[178:179], v[6:7], v[38:39]
	v_pk_mul_f32 v[180:181], v[8:9], v[40:41]
	v_pk_fma_f32 v[174:175], v[10:11], v[42:43], v[174:175]
	v_pk_fma_f32 v[176:177], v[12:13], v[44:45], v[176:177]
	v_pk_fma_f32 v[178:179], v[14:15], v[46:47], v[178:179]
	v_pk_fma_f32 v[180:181], v[16:17], v[48:49], v[180:181]
	v_pk_fma_f32 v[174:175], v[18:19], v[26:27], v[174:175]
	v_pk_fma_f32 v[176:177], v[20:21], v[28:29], v[176:177]
	v_pk_fma_f32 v[178:179], v[22:23], v[30:31], v[178:179]
	v_pk_fma_f32 v[180:181], v[24:25], v[32:33], v[180:181]
	v_pk_mul_f32 v[174:175], v[126:127], v[174:175]
	v_pk_mul_f32 v[176:177], v[128:129], v[176:177]
	v_pk_mul_f32 v[178:179], v[130:131], v[178:179]
	v_pk_mul_f32 v[180:181], v[132:133], v[180:181]
	v_cvt_pk_bf16_f32 v112, v174, v175
	v_cvt_pk_bf16_f32 v113, v176, v177
	v_cvt_pk_bf16_f32 v114, v178, v179
	v_cvt_pk_bf16_f32 v115, v180, v181
	v_add_u32_e32 v125, 0x5400, v124
	global_store_dwordx4 v125, v[112:115], s[24:25]
	v_and_b32_e32 v125, 0x1ff8, v122
	s_movk_i32 s0, 0x1ff8
	v_cmp_eq_u32_e32 vcc, s0, v125
	s_and_b64 s[0:1], s[38:39], vcc
	s_and_b64 exec, s[30:31], s[0:1]
	s_cbranch_execz .Lconv_st_a
	v_ashrrev_i32_e32 v125, 12, v122
	v_and_b32_e32 v125, -2, v125
	v_lshl_add_u32 v125, v125, 12, v120
	global_store_dwordx4 v125, v[42:45], s[12:13]
	global_store_dwordx4 v125, v[46:49], s[12:13] offset:16
	v_add_u32_e32 v125, 0x1000, v125
	global_store_dwordx4 v125, v[26:29], s[12:13]
	global_store_dwordx4 v125, v[30:33], s[12:13] offset:16
.Lconv_st_a:
	s_andn2_b64 exec, s[30:31], s[38:39]
	s_cbranch_execz .Lconv_st_b
	v_add_u32_e32 v125, 0xffffc000, v122
	v_lshrrev_b32_e32 v125, 2, v125
	v_lshl_add_u32 v125, v125, 12, v120
	global_store_dwordx4 v125, v[42:45], s[14:15]
	global_store_dwordx4 v125, v[46:49], s[14:15] offset:16
	v_add_u32_e32 v125, 0x1000, v125
	global_store_dwordx4 v125, v[26:29], s[14:15]
	global_store_dwordx4 v125, v[30:33], s[14:15] offset:16
.Lconv_st_b:
	s_mov_b64 exec, s[30:31]
	s_mov_b64 s[0:1], 0

.LBB0_558:
	s_cbranch_execnz .LBB0_455
	s_branch .LBB0_538
.LBB0_561:
	v_mad_u64_u32 v[6:7], s[0:1], v4, s34, 0
	v_mov_b32_e32 v4, v7
	v_mad_u64_u32 v[4:5], s[0:1], v5, s34, v[4:5]
	v_mov_b32_e32 v7, v4
	v_lshl_add_u64 v[0:1], v[6:7], 2, v[0:1]
	global_load_dwordx4 v[4:7], v[0:1], off
	v_lshl_add_u64 v[0:1], s[34:35], 2, v[0:1]
	s_waitcnt vmcnt(0)
	v_pk_mul_f32 v[10:11], v[8:9], v[6:7] op_sel_hi:[0,1]
	v_pk_mul_f32 v[12:13], v[8:9], v[4:5] op_sel_hi:[0,1]
	global_load_dwordx4 v[4:7], v[0:1], off
	v_ashrrev_i32_e32 v8, 3, v3
	s_waitcnt vmcnt(0)
	v_pk_mul_f32 v[0:1], v[6:7], v[2:3] op_sel_hi:[1,0]
	s_nop 0
	v_cvt_pk_bf16_f32 v1, v11, v1
	v_cvt_pk_bf16_f32 v0, v10, v0
	ds_write2_b32 v9, v0, v1 offset0:162 offset1:227
	v_lshlrev_b32_e32 v1, 5, v3
	v_pk_mul_f32 v[4:5], v[4:5], v[2:3] op_sel_hi:[1,0]
	v_mul_lo_u32 v0, v8, s76
	v_and_b32_e32 v136, 0xe0, v1
	v_add_u32_e32 v8, s11, v8
	v_cvt_pk_bf16_f32 v2, v12, v4
	v_cvt_pk_bf16_f32 v4, v13, v5
	ds_write2_b32 v9, v2, v4 offset0:32 offset1:97
	v_add3_u32 v6, 0, v0, v136
	v_ashrrev_i32_e32 v9, 31, v8
	s_waitcnt lgkmcnt(0)
	s_barrier
	ds_read2_b32 v[0:1], v6 offset1:1
	ds_read2_b32 v[2:3], v6 offset0:2 offset1:3
	ds_read2_b32 v[4:5], v6 offset0:4 offset1:5
	ds_read2_b32 v[6:7], v6 offset0:6 offset1:7
	v_mul_lo_u32 v10, s4, v9
	v_mul_lo_u32 v11, s5, v8
	v_mad_u64_u32 v[8:9], s[0:1], s4, v8, 0
	v_add3_u32 v9, v9, v10, v11
	v_lshl_add_u64 v[8:9], v[8:9], 1, s[2:3]
	s_ashr_i32 s11, s10, 31
	v_readlane_b32 s0, v242, 8
	v_lshl_add_u64 v[8:9], s[10:11], 1, v[8:9]
	s_add_i32 s17, s17, s0
	v_lshl_add_u64 v[8:9], v[8:9], 0, v[136:137]
	s_cmp_lt_i32 s17, s16
	s_waitcnt lgkmcnt(2)
	global_store_dwordx4 v[8:9], v[0:3], off
	s_waitcnt lgkmcnt(0)
	global_store_dwordx4 v[8:9], v[4:7], off offset:16
	s_barrier
	v_readlane_b32 s1, v242, 9
	s_cbranch_scc0 .LBB0_445
